# as v67 with mat 28 moved from the L1 gate/up tail to the L2 gate/up tail (tails: R1 24; L1 GU 29; L2 GU 26,28,30,31), same code placement mod 128
# speedup vs baseline: 1.0025x; 1.0025x over previous
;     __device__ __forceinline__ void ids() { lane = fresh_lane(); tid = wave * 64 + lane; }
; __device__ __forceinline__ void convert_mats(Frame& F, int m_lo, int m_hi, int gw, int NGW) {
;     ...
;             if (i1 < lim) conv_proc(vb, gain, mt.K, mt.Kp, mt.Np, mt.ilv, dst, scr, i1 - base, F.lane);
;             it = (i1 < lim) ? i1 + NGW : i1;
;         }
;         base += cnt;
;     }
; template <int L> __device__ __forceinline__ void layer_phases(Frame& F, const int lo, const int hi, const XcdBarrier& bar, const int bid) {
;     ...
;                 } else if constexpr (L == 1) { F.ids(); convert_mats(F, 27, 29, ci * NWAVES + F.wave, nidle * NWAVES); }
.Lcvc_m29_done:
	s_mov_b32 s22, s23
	s_waitcnt vmcnt(0)
	s_nop 0
	s_nop 0
	s_nop 0
	s_nop 0
	s_nop 0
	s_nop 0
	s_nop 0
	s_nop 0
	s_nop 0
	s_nop 0
	s_nop 0
	s_nop 0
	s_nop 0
	s_nop 0
	s_nop 0
	s_nop 0
	s_nop 0
	s_nop 0
	s_nop 0
	s_nop 0
	s_nop 0
	s_nop 0
	s_nop 0
	s_nop 0
	s_nop 0

;     __device__ __forceinline__ void ids() { lane = fresh_lane(); tid = wave * 64 + lane; }
; __device__ __forceinline__ void convert_mats(Frame& F, int m_lo, int m_hi, int gw, int NGW) {
;     ...
;             it = (i1 < lim) ? i1 + NGW : i1;
;         }
;         base += cnt;
;     }
; template <int L> __device__ __forceinline__ void layer_phases(Frame& F, const int lo, const int hi, const XcdBarrier& bar, const int bid) {
;     ...
;                 else if constexpr (L == 2) { F.ids(); convert_mats(F, 29, 32, ci * NWAVES + F.wave, nidle * NWAVES); }
.Lcvd_m31_done:
	s_mov_b32 s22, s23
	s_waitcnt vmcnt(0)
	s_nop 0
	s_nop 0
	s_nop 0
	s_nop 0
	s_nop 0
	s_nop 0
	s_nop 0
